# attention interior loop: redundant 9-state pad after the QK MFMAs removed (the V transpose reads and K-prefetch address setup already supply 20+ wait states before the first exp)
# speedup vs baseline: 1.0003x; 1.0003x over previous
.LBB0_106:
	v_mfma_f32_32x32x16_bf16 v[48:63], v[220:223], v[90:93], v[48:63]
	v_mfma_f32_32x32x16_bf16 v[64:79], v[228:231], v[90:93], v[64:79]
	s_lshl_b64 s[14:15], s[4:5], 17
	s_lshl_b32 s4, s37, 13
	v_lshl_add_u64 v[172:173], v[146:147], 0, s[14:15]
	s_add_i32 s4, s33, s4
	v_lshl_add_u64 v[172:173], v[172:173], 0, s[20:21]
	s_add_i32 m0, s4, 0x9000
	global_load_lds_dwordx4 v[172:173], off
	v_mfma_f32_32x32x16_bf16 v[48:63], v[224:227], v[94:97], v[48:63]
	v_mfma_f32_32x32x16_bf16 v[64:79], v[232:235], v[94:97], v[64:79]
	v_mfma_f32_32x32x16_bf16 v[48:63], v[176:179], v[98:101], v[48:63]
	v_mfma_f32_32x32x16_bf16 v[64:79], v[180:183], v[98:101], v[64:79]
	v_mfma_f32_32x32x16_bf16 v[48:63], v[184:187], v[102:105], v[48:63]
	v_mfma_f32_32x32x16_bf16 v[64:79], v[188:191], v[102:105], v[64:79]
	v_lshl_add_u32 v108, s43, 13, v131
	ds_read_b64_tr_b16 v[132:133], v108 offset:0
	ds_read_b64_tr_b16 v[134:135], v108 offset:1024
	ds_read_b64_tr_b16 v[160:161], v108 offset:64
	ds_read_b64_tr_b16 v[162:163], v108 offset:1088
	ds_read_b64_tr_b16 v[126:127], v108 offset:2048
	ds_read_b64_tr_b16 v[128:129], v108 offset:3072
	ds_read_b64_tr_b16 v[122:123], v108 offset:2112
	ds_read_b64_tr_b16 v[124:125], v108 offset:3136
	ds_read_b64_tr_b16 v[118:119], v108 offset:4096
	ds_read_b64_tr_b16 v[120:121], v108 offset:5120
	ds_read_b64_tr_b16 v[114:115], v108 offset:4160
	ds_read_b64_tr_b16 v[116:117], v108 offset:5184
	ds_read_b64_tr_b16 v[110:111], v108 offset:6144
	ds_read_b64_tr_b16 v[112:113], v108 offset:7168
	ds_read_b64_tr_b16 v[106:107], v108 offset:6208
	ds_read_b64_tr_b16 v[108:109], v108 offset:7232
	s_mul_i32 s14, s45, 0x3000
	s_add_i32 s14, s14, 16
	v_add_u32_e32 v174, s14, v149
	v_exp_f32_e32 v50, v50
	v_exp_f32_e32 v51, v51
	v_exp_f32_e32 v52, v52
	v_exp_f32_e32 v53, v53
	v_exp_f32_e32 v54, v54
	v_exp_f32_e32 v55, v55
	v_exp_f32_e32 v48, v48
	v_exp_f32_e32 v49, v49
	v_add_f32_e32 v32, v32, v50
	v_add_f32_e32 v33, v33, v51
	v_add_f32_e32 v34, v34, v52
	v_add_f32_e32 v35, v35, v53
	v_add_f32_e32 v32, v32, v54
	v_add_f32_e32 v33, v33, v55
	v_add_f32_e32 v34, v34, v48
	v_add_f32_e32 v35, v35, v49
	s_waitcnt lgkmcnt(14)
	v_cvt_pk_bf16_f32 v48, v48, v49
	v_cvt_pk_bf16_f32 v49, v50, v51
	v_cvt_pk_bf16_f32 v50, v52, v53
	v_cvt_pk_bf16_f32 v51, v54, v55
	s_nop 1
	v_mfma_f32_32x32x16_bf16 v[0:15], v[132:135], v[48:51], v[0:15]
	ds_read_b128 v[204:207], v174
	ds_read_b128 v[208:211], v174 offset:32
	ds_read_b128 v[212:215], v174 offset:6144
	v_exp_f32_e32 v56, v56
	v_exp_f32_e32 v57, v57
	v_exp_f32_e32 v58, v58
	v_exp_f32_e32 v59, v59
	v_exp_f32_e32 v60, v60
	v_exp_f32_e32 v61, v61
	v_exp_f32_e32 v62, v62
	s_waitcnt lgkmcnt(15)
	v_mfma_f32_32x32x16_bf16 v[16:31], v[160:163], v[48:51], v[16:31]
	ds_read_b128 v[216:219], v174 offset:6176
	ds_read_b128 v[220:223], v174 offset:64
	ds_read_b128 v[224:227], v174 offset:96
	v_exp_f32_e32 v63, v63
	v_exp_f32_e32 v64, v64
	v_exp_f32_e32 v65, v65
	v_exp_f32_e32 v66, v66
	v_exp_f32_e32 v67, v67
	v_exp_f32_e32 v68, v68
	v_exp_f32_e32 v69, v69
	v_add_f32_e32 v32, v32, v56
	v_add_f32_e32 v33, v33, v57
	v_add_f32_e32 v34, v34, v58
	v_add_f32_e32 v35, v35, v59
	v_add_f32_e32 v32, v32, v60
	v_add_f32_e32 v33, v33, v61
	v_add_f32_e32 v34, v34, v62
	v_add_f32_e32 v35, v35, v63
	v_cvt_pk_bf16_f32 v48, v56, v57
	v_cvt_pk_bf16_f32 v49, v58, v59
	v_cvt_pk_bf16_f32 v50, v60, v61
	v_cvt_pk_bf16_f32 v51, v62, v63
	v_exp_f32_e32 v70, v70
	v_exp_f32_e32 v71, v71
	v_exp_f32_e32 v72, v72
	s_waitcnt lgkmcnt(15)
	v_mfma_f32_32x32x16_bf16 v[0:15], v[126:129], v[48:51], v[0:15]
	ds_read_b128 v[228:231], v174 offset:6208
	ds_read_b128 v[232:235], v174 offset:6240
	v_add_u32_e32 v175, s14, v150
	ds_read_b128 v[176:179], v175
	v_exp_f32_e32 v73, v73
	v_exp_f32_e32 v74, v74
	v_exp_f32_e32 v75, v75
	v_exp_f32_e32 v76, v76
	v_exp_f32_e32 v77, v77
	v_exp_f32_e32 v78, v78
	v_exp_f32_e32 v79, v79
	s_waitcnt lgkmcnt(15)
	v_mfma_f32_32x32x16_bf16 v[16:31], v[122:125], v[48:51], v[16:31]
	ds_read_b128 v[180:183], v175 offset:6144
	v_add_u32_e32 v174, s14, v151
	ds_read_b128 v[184:187], v174
	ds_read_b128 v[188:191], v174 offset:6144
	v_add_f32_e32 v32, v32, v64
	v_add_f32_e32 v33, v33, v65
	v_add_f32_e32 v34, v34, v66
	v_add_f32_e32 v35, v35, v67
	v_add_f32_e32 v32, v32, v68
	v_add_f32_e32 v33, v33, v69
	v_add_f32_e32 v34, v34, v70
	v_add_f32_e32 v35, v35, v71
	v_cvt_pk_bf16_f32 v48, v64, v65
	v_cvt_pk_bf16_f32 v49, v66, v67
	v_cvt_pk_bf16_f32 v50, v68, v69
	v_cvt_pk_bf16_f32 v51, v70, v71
	s_nop 0
	s_waitcnt lgkmcnt(15)
	v_mfma_f32_32x32x16_bf16 v[0:15], v[118:121], v[48:51], v[0:15]
	v_mfma_f32_32x32x16_bf16 v[16:31], v[114:117], v[48:51], v[16:31]
	v_add_f32_e32 v32, v32, v72
	v_add_f32_e32 v33, v33, v73
	v_add_f32_e32 v34, v34, v74
	v_add_f32_e32 v35, v35, v75
	v_add_f32_e32 v32, v32, v76
	v_add_f32_e32 v33, v33, v77
	v_add_f32_e32 v34, v34, v78
	v_add_f32_e32 v35, v35, v79
	v_cvt_pk_bf16_f32 v48, v72, v73
	v_cvt_pk_bf16_f32 v49, v74, v75
	v_cvt_pk_bf16_f32 v50, v76, v77
	v_cvt_pk_bf16_f32 v51, v78, v79
	s_nop 0
	s_waitcnt lgkmcnt(14)
	v_mfma_f32_32x32x16_bf16 v[0:15], v[110:113], v[48:51], v[0:15]
	s_waitcnt lgkmcnt(12)
	v_mfma_f32_32x32x16_bf16 v[16:31], v[106:109], v[48:51], v[16:31]
	s_waitcnt vmcnt(0)
	s_add_i32 s49, s49, 1
	s_cmp_eq_u32 s42, s49
	s_cselect_b32 s13, s13, s45
	s_cselect_b32 s45, s45, s37
	s_cselect_b32 s37, s37, s43
	s_cselect_b32 s43, s43, s13
	s_barrier
	s_cbranch_scc1 .LBB0_113
	s_branch .Lattn_rot
